# bf16 GEMM epilogues: 76 of the 128 add-zero ops (scale 1, no bias) dropped, store-data spacers kept with s_nop
# speedup vs baseline: 1.0128x; 1.0014x over previous
; #define PG8_LAS __attribute__((address_space(3)))
; __device__ __forceinline__ unsigned cvt_pk_bf16(float lo, float hi) { typedef __bf16 bf2_t __attribute__((ext_vector_type(2))); const f32x2 v = {lo, hi}; return __builtin_bit_cast(unsigned, __builtin_convertvector(v, bf2_t)); }
;     __device__ __forceinline__ void operator()(const f32x4 (&acc)[2][2][4][2], const Unit& u, int wr, int wc, int fr, int fq, PG8_LAS unsigned char* lds) const {
;         int row0 = u.pm * BM + wr * 64 + fr; int col0 = u.pn * BM + wc * 32 + 8 * fq;
;         asm volatile("" : "+v"(row0), "+v"(col0));
;         f32x4 bv[2][2];
; #pragma unroll
;         for (int bj = 0; bj < 2; ++bj)
; #pragma unroll
;             for (int n = 0; n < 2; ++n) bv[bj][n] = bias ? *(const f32x4*)(bias + (size_t)u.e * bias_stride + col0 + bj * HALF + 4 * n) : (f32x4){0.f, 0.f, 0.f, 0.f};
; #pragma unroll
;         for (int ai = 0; ai < 2; ++ai)
; #pragma unroll
;             for (int m = 0; m < 4; ++m) { bf16_t* rowp = O + (size_t)(row0 + ai * HALF + m * 16) * ldc + col0;
; #pragma unroll
;                 for (int bj = 0; bj < 2; ++bj) { const f32x4 v0 = acc[ai][bj][m][0] * scale + bv[bj][0], v1 = acc[ai][bj][m][1] * scale + bv[bj][1];
;                     u32x4 w; w.x = cvt_pk_bf16(v0[0], v0[1]); w.y = cvt_pk_bf16(v0[2], v0[3]); w.z = cvt_pk_bf16(v1[0], v1[1]); w.w = cvt_pk_bf16(v1[2], v1[3]);
;                     *(u32x4*)(rowp + bj * HALF) = w; } }
;     }
.LBB0_173:
	v_lshl_add_u32 v140, s74, 8, v17
	v_lshl_or_b32 v134, s73, 8, v67
	v_mov_b64_e32 v[132:133], s[76:77]
	v_ashrrev_i32_e32 v135, 31, v134
	v_mad_i64_i32 v[136:137], s[38:39], v140, s75, v[132:133]
	v_lshlrev_b64 v[134:135], 1, v[134:135]
	v_pk_add_f32 v[138:139], v[126:127], 0 op_sel_hi:[1,0]
	v_pk_add_f32 v[126:127], v[124:125], 0 op_sel_hi:[1,0]
	v_lshl_add_u64 v[136:137], v[136:137], 0, v[134:135]
	v_cvt_pk_bf16_f32 v124, v128, v129
	v_cvt_pk_bf16_f32 v125, v130, v131
	v_cvt_pk_bf16_f32 v126, v126, v127
	v_cvt_pk_bf16_f32 v127, v138, v139
	global_store_dwordx4 v[136:137], v[124:127], off
	s_nop 1
	v_pk_add_f32 v[124:125], v[110:111], 0 op_sel_hi:[1,0]
	v_pk_add_f32 v[110:111], v[108:109], 0 op_sel_hi:[1,0]
	v_cvt_pk_bf16_f32 v108, v116, v117
	v_cvt_pk_bf16_f32 v109, v118, v119
	v_cvt_pk_bf16_f32 v110, v110, v111
	v_cvt_pk_bf16_f32 v111, v124, v125
	global_store_dwordx4 v[136:137], v[108:111], off offset:256
	s_nop 1
	v_add_u32_e32 v108, 16, v140
	v_mad_i64_i32 v[108:109], s[38:39], v108, s75, v[132:133]
	v_lshl_add_u64 v[116:117], v[108:109], 0, v[134:135]
	v_cvt_pk_bf16_f32 v108, v120, v121
	v_cvt_pk_bf16_f32 v109, v122, v123
	v_cvt_pk_bf16_f32 v110, v112, v113
	v_cvt_pk_bf16_f32 v111, v114, v115
	global_store_dwordx4 v[116:117], v[108:111], off
	s_nop 1
	v_pk_add_f32 v[108:109], v[94:95], 0 op_sel_hi:[1,0]
	v_pk_add_f32 v[94:95], v[92:93], 0 op_sel_hi:[1,0]
	v_cvt_pk_bf16_f32 v92, v100, v101
	v_cvt_pk_bf16_f32 v93, v102, v103
	v_cvt_pk_bf16_f32 v94, v94, v95
	v_cvt_pk_bf16_f32 v95, v108, v109
	global_store_dwordx4 v[116:117], v[92:95], off offset:256
	s_nop 1
	v_add_u32_e32 v92, 32, v140
	v_mad_i64_i32 v[92:93], s[38:39], v92, s75, v[132:133]
	v_lshl_add_u64 v[100:101], v[92:93], 0, v[134:135]
	v_cvt_pk_bf16_f32 v92, v104, v105
	v_cvt_pk_bf16_f32 v93, v106, v107
	v_cvt_pk_bf16_f32 v94, v96, v97
	v_cvt_pk_bf16_f32 v95, v98, v99
	global_store_dwordx4 v[100:101], v[92:95], off
	s_nop 1
	v_pk_add_f32 v[92:93], v[78:79], 0 op_sel_hi:[1,0]
	v_pk_add_f32 v[78:79], v[76:77], 0 op_sel_hi:[1,0]
	v_cvt_pk_bf16_f32 v76, v84, v85
	v_cvt_pk_bf16_f32 v77, v86, v87
	v_cvt_pk_bf16_f32 v78, v78, v79
	v_cvt_pk_bf16_f32 v79, v92, v93
	global_store_dwordx4 v[100:101], v[76:79], off offset:256
	s_nop 1
	v_add_u32_e32 v76, 48, v140
	v_mad_i64_i32 v[76:77], s[38:39], v76, s75, v[132:133]
	v_lshl_add_u64 v[84:85], v[76:77], 0, v[134:135]
	v_cvt_pk_bf16_f32 v76, v88, v89
	v_cvt_pk_bf16_f32 v77, v90, v91
	v_cvt_pk_bf16_f32 v78, v80, v81
	v_cvt_pk_bf16_f32 v79, v82, v83
	global_store_dwordx4 v[84:85], v[76:79], off
	s_nop 1
	v_pk_add_f32 v[76:77], v[70:71], 0 op_sel_hi:[1,0]
	v_pk_add_f32 v[70:71], v[68:69], 0 op_sel_hi:[1,0]
	v_cvt_pk_bf16_f32 v68, v72, v73
	v_cvt_pk_bf16_f32 v69, v74, v75
	v_cvt_pk_bf16_f32 v70, v70, v71
	v_cvt_pk_bf16_f32 v71, v76, v77
	global_store_dwordx4 v[84:85], v[68:71], off offset:256
	s_nop 1
	v_add_u32_e32 v68, 0x80, v140
	v_mad_i64_i32 v[68:69], s[38:39], v68, s75, v[132:133]
	v_pk_add_f32 v[70:71], v[36:37], 0 op_sel_hi:[1,0]
	v_pk_add_f32 v[36:37], v[34:35], 0 op_sel_hi:[1,0]
	v_lshl_add_u64 v[68:69], v[68:69], 0, v[134:135]
	v_cvt_pk_bf16_f32 v34, v46, v47
	v_cvt_pk_bf16_f32 v35, v48, v49
	v_cvt_pk_bf16_f32 v36, v36, v37
	v_cvt_pk_bf16_f32 v37, v70, v71
	global_store_dwordx4 v[68:69], v[34:37], off
	v_pk_add_f32 v[46:47], v[64:65], 0 op_sel_hi:[1,0]
	v_pk_add_f32 v[48:49], v[62:63], 0 op_sel_hi:[1,0]
	v_cvt_pk_bf16_f32 v34, v58, v59
	v_cvt_pk_bf16_f32 v35, v60, v61
	v_cvt_pk_bf16_f32 v36, v48, v49
	v_cvt_pk_bf16_f32 v37, v46, v47
	global_store_dwordx4 v[68:69], v[34:37], off offset:256
	s_nop 1
	v_add_u32_e32 v34, 0x90, v140
	v_mad_i64_i32 v[34:35], s[38:39], v34, s75, v[132:133]
	v_pk_add_f32 v[36:37], v[20:21], 0 op_sel_hi:[1,0]
	v_pk_add_f32 v[20:21], v[18:19], 0 op_sel_hi:[1,0]
	v_lshl_add_u64 v[34:35], v[34:35], 0, v[134:135]
	v_cvt_pk_bf16_f32 v18, v22, v23
	v_cvt_pk_bf16_f32 v19, v24, v25
	v_cvt_pk_bf16_f32 v20, v20, v21
	v_cvt_pk_bf16_f32 v21, v36, v37
	global_store_dwordx4 v[34:35], v[18:21], off
	v_pk_add_f32 v[22:23], v[56:57], 0 op_sel_hi:[1,0]
	v_pk_add_f32 v[24:25], v[54:55], 0 op_sel_hi:[1,0]
	s_and_b64 vcc, exec, s[40:41]
	v_cvt_pk_bf16_f32 v18, v50, v51
	v_cvt_pk_bf16_f32 v19, v52, v53
	v_cvt_pk_bf16_f32 v20, v24, v25
	v_cvt_pk_bf16_f32 v21, v22, v23
	global_store_dwordx4 v[34:35], v[18:21], off offset:256
	s_nop 1
	v_add_u32_e32 v18, 0xa0, v140
	v_mad_i64_i32 v[18:19], s[38:39], v18, s75, v[132:133]
	v_pk_add_f32 v[20:21], v[10:11], 0 op_sel_hi:[1,0]
	v_pk_add_f32 v[10:11], v[8:9], 0 op_sel_hi:[1,0]
	v_lshl_add_u64 v[18:19], v[18:19], 0, v[134:135]
	v_cvt_pk_bf16_f32 v8, v12, v13
	v_cvt_pk_bf16_f32 v9, v14, v15
	v_cvt_pk_bf16_f32 v10, v10, v11
	v_cvt_pk_bf16_f32 v11, v20, v21
	global_store_dwordx4 v[18:19], v[8:11], off
	v_pk_add_f32 v[12:13], v[44:45], 0 op_sel_hi:[1,0]
	v_pk_add_f32 v[14:15], v[42:43], 0 op_sel_hi:[1,0]
	s_nop 0
	v_cvt_pk_bf16_f32 v8, v38, v39
	v_cvt_pk_bf16_f32 v9, v40, v41
	v_cvt_pk_bf16_f32 v10, v14, v15
	v_cvt_pk_bf16_f32 v11, v12, v13
	global_store_dwordx4 v[18:19], v[8:11], off offset:256
	s_nop 1
	v_add_u32_e32 v8, 0xb0, v140
	v_mad_i64_i32 v[8:9], s[38:39], v8, s75, v[132:133]
	v_pk_add_f32 v[10:11], v[2:3], 0 op_sel_hi:[1,0]
	v_pk_add_f32 v[2:3], v[0:1], 0 op_sel_hi:[1,0]
	v_lshl_add_u64 v[8:9], v[8:9], 0, v[134:135]
	v_cvt_pk_bf16_f32 v0, v4, v5
	v_cvt_pk_bf16_f32 v1, v6, v7
	v_cvt_pk_bf16_f32 v2, v2, v3
	v_cvt_pk_bf16_f32 v3, v10, v11
	global_store_dwordx4 v[8:9], v[0:3], off
	v_pk_add_f32 v[4:5], v[32:33], 0 op_sel_hi:[1,0]
	v_pk_add_f32 v[6:7], v[30:31], 0 op_sel_hi:[1,0]
	s_mov_b64 s[38:39], -1
	v_cvt_pk_bf16_f32 v0, v26, v27
	v_cvt_pk_bf16_f32 v1, v28, v29
	v_cvt_pk_bf16_f32 v2, v6, v7
	v_cvt_pk_bf16_f32 v3, v4, v5
	global_store_dwordx4 v[8:9], v[0:3], off offset:256
	s_cbranch_vccnz .LBB0_152
	s_andn2_b64 vcc, exec, s[2:3]
	s_cbranch_vccnz .LBB0_151
	s_barrier
	s_branch .LBB0_151

; #define PG8_LAS __attribute__((address_space(3)))
; __device__ __forceinline__ unsigned cvt_pk_bf16(float lo, float hi) { typedef __bf16 bf2_t __attribute__((ext_vector_type(2))); const f32x2 v = {lo, hi}; return __builtin_bit_cast(unsigned, __builtin_convertvector(v, bf2_t)); }
;     __device__ __forceinline__ void operator()(const f32x4 (&acc)[2][2][4][2], const Unit& u, int wr, int wc, int fr, int fq, PG8_LAS unsigned char* lds) const {
;         int row0 = u.pm * BM + wr * 64 + fr; int col0 = u.pn * BM + wc * 32 + 8 * fq;
;         asm volatile("" : "+v"(row0), "+v"(col0));
;         f32x4 bv[2][2];
; #pragma unroll
;         for (int bj = 0; bj < 2; ++bj)
; #pragma unroll
;             for (int n = 0; n < 2; ++n) bv[bj][n] = bias ? *(const f32x4*)(bias + (size_t)u.e * bias_stride + col0 + bj * HALF + 4 * n) : (f32x4){0.f, 0.f, 0.f, 0.f};
; #pragma unroll
;         for (int ai = 0; ai < 2; ++ai)
; #pragma unroll
;             for (int m = 0; m < 4; ++m) { bf16_t* rowp = O + (size_t)(row0 + ai * HALF + m * 16) * ldc + col0;
; #pragma unroll
;                 for (int bj = 0; bj < 2; ++bj) { const f32x4 v0 = acc[ai][bj][m][0] * scale + bv[bj][0], v1 = acc[ai][bj][m][1] * scale + bv[bj][1];
;                     u32x4 w; w.x = cvt_pk_bf16(v0[0], v0[1]); w.y = cvt_pk_bf16(v0[2], v0[3]); w.z = cvt_pk_bf16(v1[0], v1[1]); w.w = cvt_pk_bf16(v1[2], v1[3]);
;                     *(u32x4*)(rowp + bj * HALF) = w; } }
;     }
.LBB0_737:
	v_lshl_add_u32 v132, s74, 8, v17
	v_lshl_or_b32 v134, s73, 8, v67
	v_readlane_b32 s38, v252, 9
	v_ashrrev_i32_e32 v133, 31, v132
	v_lshlrev_b64 v[132:133], 11, v[132:133]
	v_readlane_b32 s39, v252, 10
	v_ashrrev_i32_e32 v135, 31, v134
	v_lshl_add_u64 v[132:133], s[38:39], 0, v[132:133]
	v_lshl_add_u64 v[132:133], v[134:135], 1, v[132:133]
	v_pk_add_f32 v[134:135], v[126:127], 0 op_sel_hi:[1,0]
	v_pk_add_f32 v[126:127], v[124:125], 0 op_sel_hi:[1,0]
	v_cvt_pk_bf16_f32 v124, v128, v129
	v_cvt_pk_bf16_f32 v125, v130, v131
	v_cvt_pk_bf16_f32 v126, v126, v127
	v_cvt_pk_bf16_f32 v127, v134, v135
	global_store_dwordx4 v[132:133], v[124:127], off
	s_nop 1
	v_pk_add_f32 v[124:125], v[110:111], 0 op_sel_hi:[1,0]
	v_pk_add_f32 v[110:111], v[108:109], 0 op_sel_hi:[1,0]
	v_cvt_pk_bf16_f32 v108, v116, v117
	v_cvt_pk_bf16_f32 v109, v118, v119
	v_cvt_pk_bf16_f32 v110, v110, v111
	v_cvt_pk_bf16_f32 v111, v124, v125
	global_store_dwordx4 v[132:133], v[108:111], off offset:256
	s_nop 0
	s_mov_b32 s23, 0x8000
	v_cvt_pk_bf16_f32 v108, v120, v121
	v_cvt_pk_bf16_f32 v109, v122, v123
	v_cvt_pk_bf16_f32 v110, v112, v113
	v_add_co_u32_e32 v112, vcc, s23, v132
	v_cvt_pk_bf16_f32 v111, v114, v115
	s_nop 0
	v_addc_co_u32_e32 v113, vcc, 0, v133, vcc
	s_mov_b64 s[38:39], 0x8000
	global_store_dwordx4 v[112:113], v[108:111], off
	s_nop 1
	v_pk_add_f32 v[108:109], v[94:95], 0 op_sel_hi:[1,0]
	v_pk_add_f32 v[94:95], v[92:93], 0 op_sel_hi:[1,0]
	v_lshl_add_u64 v[116:117], v[132:133], 0, s[38:39]
	v_cvt_pk_bf16_f32 v92, v100, v101
	v_cvt_pk_bf16_f32 v93, v102, v103
	v_cvt_pk_bf16_f32 v94, v94, v95
	v_cvt_pk_bf16_f32 v95, v108, v109
	global_store_dwordx4 v[116:117], v[92:95], off offset:256
	s_nop 0
	s_mov_b32 s23, 0x10000
	v_cvt_pk_bf16_f32 v92, v104, v105
	v_cvt_pk_bf16_f32 v93, v106, v107
	v_cvt_pk_bf16_f32 v94, v96, v97
	v_add_co_u32_e32 v96, vcc, s23, v132
	v_cvt_pk_bf16_f32 v95, v98, v99
	s_nop 0
	v_addc_co_u32_e32 v97, vcc, 0, v133, vcc
	s_mov_b64 s[38:39], 0x10000
	global_store_dwordx4 v[96:97], v[92:95], off
	s_nop 1
	v_pk_add_f32 v[92:93], v[78:79], 0 op_sel_hi:[1,0]
	v_pk_add_f32 v[78:79], v[76:77], 0 op_sel_hi:[1,0]
	v_lshl_add_u64 v[100:101], v[132:133], 0, s[38:39]
	v_cvt_pk_bf16_f32 v76, v84, v85
	v_cvt_pk_bf16_f32 v77, v86, v87
	v_cvt_pk_bf16_f32 v78, v78, v79
	v_cvt_pk_bf16_f32 v79, v92, v93
	global_store_dwordx4 v[100:101], v[76:79], off offset:256
	s_nop 0
	s_mov_b32 s23, 0x18000
	v_cvt_pk_bf16_f32 v76, v88, v89
	v_cvt_pk_bf16_f32 v77, v90, v91
	v_cvt_pk_bf16_f32 v78, v80, v81
	v_add_co_u32_e32 v80, vcc, s23, v132
	v_cvt_pk_bf16_f32 v79, v82, v83
	s_nop 0
	v_addc_co_u32_e32 v81, vcc, 0, v133, vcc
	s_mov_b64 s[38:39], 0x18000
	global_store_dwordx4 v[80:81], v[76:79], off
	s_nop 1
	v_pk_add_f32 v[76:77], v[70:71], 0 op_sel_hi:[1,0]
	v_pk_add_f32 v[70:71], v[68:69], 0 op_sel_hi:[1,0]
	v_lshl_add_u64 v[84:85], v[132:133], 0, s[38:39]
	v_cvt_pk_bf16_f32 v68, v72, v73
	v_cvt_pk_bf16_f32 v69, v74, v75
	v_cvt_pk_bf16_f32 v70, v70, v71
	v_cvt_pk_bf16_f32 v71, v76, v77
	s_mov_b32 s23, 0x40000
	global_store_dwordx4 v[84:85], v[68:71], off offset:256
	s_nop 0
	s_mov_b64 s[38:39], 0x40000
	v_pk_add_f32 v[70:71], v[44:45], 0 op_sel_hi:[1,0]
	v_pk_add_f32 v[44:45], v[42:43], 0 op_sel_hi:[1,0]
	v_cvt_pk_bf16_f32 v42, v46, v47
	v_add_co_u32_e32 v46, vcc, s23, v132
	v_cvt_pk_bf16_f32 v43, v48, v49
	v_cvt_pk_bf16_f32 v44, v44, v45
	v_cvt_pk_bf16_f32 v45, v70, v71
	v_addc_co_u32_e32 v47, vcc, 0, v133, vcc
	global_store_dwordx4 v[46:47], v[42:45], off
	v_pk_add_f32 v[46:47], v[64:65], 0 op_sel_hi:[1,0]
	v_pk_add_f32 v[48:49], v[62:63], 0 op_sel_hi:[1,0]
	v_lshl_add_u64 v[68:69], v[132:133], 0, s[38:39]
	v_cvt_pk_bf16_f32 v42, v58, v59
	v_cvt_pk_bf16_f32 v43, v60, v61
	v_cvt_pk_bf16_f32 v44, v48, v49
	v_cvt_pk_bf16_f32 v45, v46, v47
	s_mov_b32 s23, 0x48000
	global_store_dwordx4 v[68:69], v[42:45], off offset:256
	s_nop 0
	s_mov_b64 s[38:39], 0x48000
	v_pk_add_f32 v[44:45], v[20:21], 0 op_sel_hi:[1,0]
	v_pk_add_f32 v[20:21], v[18:19], 0 op_sel_hi:[1,0]
	v_cvt_pk_bf16_f32 v18, v30, v31
	v_add_co_u32_e32 v30, vcc, s23, v132
	v_cvt_pk_bf16_f32 v19, v32, v33
	v_cvt_pk_bf16_f32 v20, v20, v21
	v_cvt_pk_bf16_f32 v21, v44, v45
	v_addc_co_u32_e32 v31, vcc, 0, v133, vcc
	global_store_dwordx4 v[30:31], v[18:21], off
	v_pk_add_f32 v[30:31], v[56:57], 0 op_sel_hi:[1,0]
	v_pk_add_f32 v[32:33], v[54:55], 0 op_sel_hi:[1,0]
	v_lshl_add_u64 v[42:43], v[132:133], 0, s[38:39]
	v_cvt_pk_bf16_f32 v18, v50, v51
	v_cvt_pk_bf16_f32 v19, v52, v53
	v_cvt_pk_bf16_f32 v20, v32, v33
	v_cvt_pk_bf16_f32 v21, v30, v31
	s_mov_b32 s23, 0x50000
	global_store_dwordx4 v[42:43], v[18:21], off offset:256
	s_nop 0
	s_mov_b64 s[38:39], 0x50000
	v_pk_add_f32 v[20:21], v[10:11], 0 op_sel_hi:[1,0]
	v_pk_add_f32 v[10:11], v[8:9], 0 op_sel_hi:[1,0]
	v_cvt_pk_bf16_f32 v8, v12, v13
	v_add_co_u32_e32 v12, vcc, s23, v132
	v_cvt_pk_bf16_f32 v9, v14, v15
	v_cvt_pk_bf16_f32 v10, v10, v11
	v_cvt_pk_bf16_f32 v11, v20, v21
	v_addc_co_u32_e32 v13, vcc, 0, v133, vcc
	global_store_dwordx4 v[12:13], v[8:11], off
	v_pk_add_f32 v[12:13], v[40:41], 0 op_sel_hi:[1,0]
	v_pk_add_f32 v[14:15], v[38:39], 0 op_sel_hi:[1,0]
	v_lshl_add_u64 v[18:19], v[132:133], 0, s[38:39]
	v_cvt_pk_bf16_f32 v8, v34, v35
	v_cvt_pk_bf16_f32 v9, v36, v37
	v_cvt_pk_bf16_f32 v10, v14, v15
	v_cvt_pk_bf16_f32 v11, v12, v13
	s_mov_b32 s23, 0x58000
	global_store_dwordx4 v[18:19], v[8:11], off offset:256
	s_nop 0
	s_mov_b64 s[38:39], 0x58000
	v_pk_add_f32 v[10:11], v[2:3], 0 op_sel_hi:[1,0]
	v_pk_add_f32 v[2:3], v[0:1], 0 op_sel_hi:[1,0]
	v_cvt_pk_bf16_f32 v0, v4, v5
	v_add_co_u32_e32 v4, vcc, s23, v132
	v_cvt_pk_bf16_f32 v1, v6, v7
	v_cvt_pk_bf16_f32 v2, v2, v3
	v_cvt_pk_bf16_f32 v3, v10, v11
	v_addc_co_u32_e32 v5, vcc, 0, v133, vcc
	global_store_dwordx4 v[4:5], v[0:3], off
	v_pk_add_f32 v[4:5], v[28:29], 0 op_sel_hi:[1,0]
	v_pk_add_f32 v[6:7], v[26:27], 0 op_sel_hi:[1,0]
	v_lshl_add_u64 v[8:9], v[132:133], 0, s[38:39]
	v_cvt_pk_bf16_f32 v0, v22, v23
	v_cvt_pk_bf16_f32 v1, v24, v25
	v_cvt_pk_bf16_f32 v2, v6, v7
	v_cvt_pk_bf16_f32 v3, v4, v5
	s_and_b64 vcc, exec, s[40:41]
	s_mov_b64 s[38:39], -1
	global_store_dwordx4 v[8:9], v[0:3], off offset:256
	s_cbranch_vccnz .LBB0_712
	s_andn2_b64 vcc, exec, s[2:3]
	s_cbranch_vccnz .LBB0_711
	s_barrier
	s_branch .LBB0_711

; #define PG8_LAS __attribute__((address_space(3)))
; __device__ __forceinline__ unsigned pk4_fp8(float a, float b, float c, float d) { int w = 0; w = __builtin_amdgcn_cvt_pk_fp8_f32(a, b, w, false); w = __builtin_amdgcn_cvt_pk_fp8_f32(c, d, w, true); return (unsigned)w; }
; __device__ __forceinline__ unsigned pk4_fp8(float a, float b, float c, float d) { int w = 0; w = __builtin_amdgcn_cvt_pk_fp8_f32(a, b, w, false); w = __builtin_amdgcn_cvt_pk_fp8_f32(c, d, w, true); return (unsigned)w; }
;     __device__ __forceinline__ void operator()(const f32x4 (&acc)[2][2][4][2], const Unit& u, int wr, int wc, int fr, int fq, PG8_LAS unsigned char* lds) const {
;         int row0 = u.pm * BM + wr * 64 + fr; int col0 = u.pn * BM + wc * 32 + 8 * fq;
;         asm volatile("" : "+v"(row0), "+v"(col0));
;         f32x4 bv[2][2];
; #pragma unroll
;         for (int bj = 0; bj < 2; ++bj)
; #pragma unroll
;             for (int n = 0; n < 2; ++n) bv[bj][n] = *(const PG8_LAS f32x4*)(lds + BIAS_LDS_OFF + u.par * 1024 + (wc * 32 + 8 * fq + bj * HALF + 4 * n) * 4) * out_scale;
;         const float sc = scale * out_scale;
;         const int odd = fq & 1; unsigned char* obase = O + (size_t)(row0 + odd * 16) * ldc + (col0 - 8 * odd);
; #pragma unroll
;         for (int ai = 0; ai < 2; ++ai)
; #pragma unroll
;             for (int mp = 0; mp < 2; ++mp) { unsigned char* rowp = obase + (size_t)(ai * HALF + mp * 32) * ldc;
; #pragma unroll
;                 for (int bj = 0; bj < 2; ++bj) { u32x2 w[2];
; #pragma unroll
;                     for (int q = 0; q < 2; ++q) { const int m = 2 * mp + q; const f32x4 v0 = acc[ai][bj][m][0] * sc + bv[bj][0], v1 = acc[ai][bj][m][1] * sc + bv[bj][1];
;                         w[q].x = pk4_fp8(v0[0], v0[1], v0[2], v0[3]); w[q].y = pk4_fp8(v1[0], v1[1], v1[2], v1[3]); }
;                     const auto sx = __builtin_amdgcn_permlane16_swap(w[0].x, w[1].x, false, false), sy = __builtin_amdgcn_permlane16_swap(w[0].y, w[1].y, false, false);
;                     u32x4 o; o.x = sx[0]; o.y = sy[0]; o.z = sx[1]; o.w = sy[1];
;                     *(u32x4*)(rowp + bj * HALF) = o; } }
;     }
.LBB0_1126:
	v_lshl_add_u32 v18, s56, 8, v17
	v_lshl_or_b32 v20, s2, 8, v67
	v_lshl_add_u32 v19, s90, 10, v231
	ds_read_b128 v[0:3], v19
	ds_read_b128 v[4:7], v19 offset:16
	s_mov_b32 s2, 0x42000000
	v_add_u32_e32 v18, v18, v226
	v_sub_u32_e32 v20, v20, v227
	s_waitcnt lgkmcnt(0)
	v_pk_mul_f32 v[14:15], v[2:3], s[2:3] op_sel_hi:[1,0]
	v_pk_mul_f32 v[10:11], v[0:1], s[2:3] op_sel_hi:[1,0]
	v_pk_mul_f32 v[12:13], v[6:7], s[2:3] op_sel_hi:[1,0]
	v_pk_mul_f32 v[8:9], v[4:5], s[2:3] op_sel_hi:[1,0]
	ds_read_b128 v[0:3], v19 offset:512
	ds_read_b128 v[4:7], v19 offset:528
	v_ashrrev_i32_e32 v19, 31, v18
	v_lshlrev_b64 v[18:19], 10, v[18:19]
	v_ashrrev_i32_e32 v21, 31, v20
	s_waitcnt lgkmcnt(0)
	v_pk_mul_f32 v[2:3], v[2:3], s[2:3] op_sel_hi:[1,0]
	v_pk_mul_f32 v[0:1], v[0:1], s[2:3] op_sel_hi:[1,0]
	v_pk_mul_f32 v[6:7], v[6:7], s[2:3] op_sel_hi:[1,0]
	v_pk_mul_f32 v[4:5], v[4:5], s[2:3] op_sel_hi:[1,0]
	v_readlane_b32 s2, v252, 33
	v_readlane_b32 s3, v252, 34
	s_mov_b32 s40, 0x3e000000
	v_pk_fma_f32 v[24:25], v[192:193], s[40:41], v[10:11] op_sel_hi:[1,0,1]
	v_lshl_add_u64 v[18:19], s[2:3], 0, v[18:19]
	v_lshl_add_u64 v[18:19], v[18:19], 0, v[20:21]
	v_pk_fma_f32 v[28:29], v[188:189], s[40:41], v[8:9] op_sel_hi:[1,0,1]
	v_cvt_pk_fp8_f32 v20, v24, v25
	v_cvt_pk_fp8_f32 v21, v28, v29
	v_pk_fma_f32 v[22:23], v[194:195], s[40:41], v[14:15] op_sel_hi:[1,0,1]
	v_pk_fma_f32 v[26:27], v[190:191], s[40:41], v[12:13] op_sel_hi:[1,0,1]
	v_cvt_pk_fp8_f32 v20, v22, v23 op_sel:[0,0,1]
	v_cvt_pk_fp8_f32 v21, v26, v27 op_sel:[0,0,1]
	v_pk_fma_f32 v[26:27], v[184:185], s[40:41], v[10:11] op_sel_hi:[1,0,1]
	v_pk_fma_f32 v[30:31], v[180:181], s[40:41], v[8:9] op_sel_hi:[1,0,1]
	v_cvt_pk_fp8_f32 v22, v26, v27
	v_cvt_pk_fp8_f32 v23, v30, v31
	v_pk_fma_f32 v[24:25], v[186:187], s[40:41], v[14:15] op_sel_hi:[1,0,1]
	v_pk_fma_f32 v[28:29], v[182:183], s[40:41], v[12:13] op_sel_hi:[1,0,1]
	v_cvt_pk_fp8_f32 v22, v24, v25 op_sel:[0,0,1]
	v_cvt_pk_fp8_f32 v23, v28, v29 op_sel:[0,0,1]
	v_pk_fma_f32 v[24:25], v[176:177], s[40:41], v[0:1] op_sel_hi:[1,0,1]
	v_pk_fma_f32 v[28:29], v[172:173], s[40:41], v[4:5] op_sel_hi:[1,0,1]
	v_permlane16_swap_b32_e32 v20, v22
	v_permlane16_swap_b32_e32 v21, v23
	global_store_dwordx4 v[18:19], v[20:23], off
	v_pk_fma_f32 v[26:27], v[174:175], s[40:41], v[6:7] op_sel_hi:[1,0,1]
	v_pk_fma_f32 v[30:31], v[164:165], s[40:41], v[4:5] op_sel_hi:[1,0,1]
	v_cvt_pk_fp8_f32 v20, v24, v25
	v_cvt_pk_fp8_f32 v21, v28, v29
	v_pk_fma_f32 v[22:23], v[178:179], s[40:41], v[2:3] op_sel_hi:[1,0,1]
	v_pk_fma_f32 v[24:25], v[170:171], s[40:41], v[2:3] op_sel_hi:[1,0,1]
	v_cvt_pk_fp8_f32 v20, v22, v23 op_sel:[0,0,1]
	v_cvt_pk_fp8_f32 v21, v26, v27 op_sel:[0,0,1]
	v_pk_fma_f32 v[26:27], v[168:169], s[40:41], v[0:1] op_sel_hi:[1,0,1]
	v_cvt_pk_fp8_f32 v22, v26, v27
	v_cvt_pk_fp8_f32 v23, v30, v31
	v_pk_fma_f32 v[28:29], v[166:167], s[40:41], v[6:7] op_sel_hi:[1,0,1]
	v_pk_fma_f32 v[26:27], v[158:159], s[40:41], v[12:13] op_sel_hi:[1,0,1]
	v_cvt_pk_fp8_f32 v22, v24, v25 op_sel:[0,0,1]
	v_cvt_pk_fp8_f32 v23, v28, v29 op_sel:[0,0,1]
	v_pk_fma_f32 v[24:25], v[160:161], s[40:41], v[10:11] op_sel_hi:[1,0,1]
	v_pk_fma_f32 v[28:29], v[156:157], s[40:41], v[8:9] op_sel_hi:[1,0,1]
	v_permlane16_swap_b32_e32 v20, v22
	v_permlane16_swap_b32_e32 v21, v23
	global_store_dwordx4 v[18:19], v[20:23], off offset:128
	v_pk_fma_f32 v[30:31], v[148:149], s[40:41], v[8:9] op_sel_hi:[1,0,1]
	s_mov_b32 s2, 0x8000
	v_cvt_pk_fp8_f32 v20, v24, v25
	v_cvt_pk_fp8_f32 v21, v28, v29
	v_pk_fma_f32 v[22:23], v[162:163], s[40:41], v[14:15] op_sel_hi:[1,0,1]
	v_pk_fma_f32 v[24:25], v[154:155], s[40:41], v[14:15] op_sel_hi:[1,0,1]
	v_cvt_pk_fp8_f32 v20, v22, v23 op_sel:[0,0,1]
	v_cvt_pk_fp8_f32 v21, v26, v27 op_sel:[0,0,1]
	v_pk_fma_f32 v[26:27], v[152:153], s[40:41], v[10:11] op_sel_hi:[1,0,1]
	v_cvt_pk_fp8_f32 v22, v26, v27
	v_cvt_pk_fp8_f32 v23, v30, v31
	v_pk_fma_f32 v[28:29], v[150:151], s[40:41], v[12:13] op_sel_hi:[1,0,1]
	v_pk_fma_f32 v[26:27], v[144:145], s[40:41], v[0:1] op_sel_hi:[1,0,1]
	v_cvt_pk_fp8_f32 v22, v24, v25 op_sel:[0,0,1]
	v_cvt_pk_fp8_f32 v23, v28, v29 op_sel:[0,0,1]
	v_add_co_u32_e32 v24, vcc, s2, v18
	v_permlane16_swap_b32_e32 v20, v22
	v_permlane16_swap_b32_e32 v21, v23
	v_addc_co_u32_e32 v25, vcc, 0, v19, vcc
	global_store_dwordx4 v[24:25], v[20:23], off
	v_pk_fma_f32 v[30:31], v[140:141], s[40:41], v[4:5] op_sel_hi:[1,0,1]
	v_pk_fma_f32 v[28:29], v[142:143], s[40:41], v[6:7] op_sel_hi:[1,0,1]
	v_cvt_pk_fp8_f32 v20, v26, v27
	v_cvt_pk_fp8_f32 v21, v30, v31
	v_pk_fma_f32 v[22:23], v[146:147], s[40:41], v[2:3] op_sel_hi:[1,0,1]
	v_pk_fma_f32 v[32:33], v[132:133], s[40:41], v[4:5] op_sel_hi:[1,0,1]
	v_cvt_pk_fp8_f32 v20, v22, v23 op_sel:[0,0,1]
	v_cvt_pk_fp8_f32 v21, v28, v29 op_sel:[0,0,1]
	v_pk_fma_f32 v[28:29], v[136:137], s[40:41], v[0:1] op_sel_hi:[1,0,1]
	v_cvt_pk_fp8_f32 v22, v28, v29
	v_cvt_pk_fp8_f32 v23, v32, v33
	v_pk_fma_f32 v[26:27], v[138:139], s[40:41], v[2:3] op_sel_hi:[1,0,1]
; __device__ __forceinline__ unsigned pk4_fp8(float a, float b, float c, float d) { int w = 0; w = __builtin_amdgcn_cvt_pk_fp8_f32(a, b, w, false); w = __builtin_amdgcn_cvt_pk_fp8_f32(c, d, w, true); return (unsigned)w; }
; __device__ __forceinline__ unsigned pk4_fp8(float a, float b, float c, float d) { int w = 0; w = __builtin_amdgcn_cvt_pk_fp8_f32(a, b, w, false); w = __builtin_amdgcn_cvt_pk_fp8_f32(c, d, w, true); return (unsigned)w; }
;     __device__ __forceinline__ void operator()(const f32x4 (&acc)[2][2][4][2], const Unit& u, int wr, int wc, int fr, int fq, PG8_LAS unsigned char* lds) const {
;     ...
;                     for (int q = 0; q < 2; ++q) { const int m = 2 * mp + q; const f32x4 v0 = acc[ai][bj][m][0] * sc + bv[bj][0], v1 = acc[ai][bj][m][1] * sc + bv[bj][1];
;                         w[q].x = pk4_fp8(v0[0], v0[1], v0[2], v0[3]); w[q].y = pk4_fp8(v1[0], v1[1], v1[2], v1[3]); }
;                     const auto sx = __builtin_amdgcn_permlane16_swap(w[0].x, w[1].x, false, false), sy = __builtin_amdgcn_permlane16_swap(w[0].y, w[1].y, false, false);
;                     u32x4 o; o.x = sx[0]; o.y = sy[0]; o.z = sx[1]; o.w = sy[1];
;                     *(u32x4*)(rowp + bj * HALF) = o; } }
;     }
	v_pk_fma_f32 v[30:31], v[134:135], s[40:41], v[6:7] op_sel_hi:[1,0,1]
	v_cvt_pk_fp8_f32 v22, v26, v27 op_sel:[0,0,1]
	v_cvt_pk_fp8_f32 v23, v30, v31 op_sel:[0,0,1]
	v_pk_fma_f32 v[28:29], v[124:125], s[40:41], v[8:9] op_sel_hi:[1,0,1]
	v_pk_fma_f32 v[26:27], v[126:127], s[40:41], v[12:13] op_sel_hi:[1,0,1]
	v_permlane16_swap_b32_e32 v20, v22
	v_permlane16_swap_b32_e32 v21, v23
	global_store_dwordx4 v[24:25], v[20:23], off offset:128
	v_pk_fma_f32 v[24:25], v[128:129], s[40:41], v[10:11] op_sel_hi:[1,0,1]
	v_pk_fma_f32 v[30:31], v[108:109], s[40:41], v[8:9] op_sel_hi:[1,0,1]
	v_cvt_pk_fp8_f32 v20, v24, v25
	v_cvt_pk_fp8_f32 v21, v28, v29
	v_pk_fma_f32 v[22:23], v[130:131], s[40:41], v[14:15] op_sel_hi:[1,0,1]
	v_pk_fma_f32 v[24:25], v[114:115], s[40:41], v[14:15] op_sel_hi:[1,0,1]
	v_cvt_pk_fp8_f32 v20, v22, v23 op_sel:[0,0,1]
	v_cvt_pk_fp8_f32 v21, v26, v27 op_sel:[0,0,1]
	v_pk_fma_f32 v[26:27], v[112:113], s[40:41], v[10:11] op_sel_hi:[1,0,1]
	v_cvt_pk_fp8_f32 v22, v26, v27
	v_cvt_pk_fp8_f32 v23, v30, v31
	v_pk_fma_f32 v[28:29], v[110:111], s[40:41], v[12:13] op_sel_hi:[1,0,1]
	s_mov_b32 s2, 0x20000
	v_cvt_pk_fp8_f32 v22, v24, v25 op_sel:[0,0,1]
	v_cvt_pk_fp8_f32 v23, v28, v29 op_sel:[0,0,1]
	v_add_co_u32_e32 v24, vcc, s2, v18
	v_permlane16_swap_b32_e32 v20, v22
	v_permlane16_swap_b32_e32 v21, v23
	v_addc_co_u32_e32 v25, vcc, 0, v19, vcc
	global_store_dwordx4 v[24:25], v[20:23], off
	v_pk_fma_f32 v[26:27], v[120:121], s[40:41], v[0:1] op_sel_hi:[1,0,1]
	v_pk_fma_f32 v[30:31], v[116:117], s[40:41], v[4:5] op_sel_hi:[1,0,1]
	v_cvt_pk_fp8_f32 v20, v26, v27
	v_cvt_pk_fp8_f32 v21, v30, v31
	v_pk_fma_f32 v[22:23], v[122:123], s[40:41], v[2:3] op_sel_hi:[1,0,1]
	v_pk_fma_f32 v[28:29], v[118:119], s[40:41], v[6:7] op_sel_hi:[1,0,1]
	v_cvt_pk_fp8_f32 v20, v22, v23 op_sel:[0,0,1]
	v_cvt_pk_fp8_f32 v21, v28, v29 op_sel:[0,0,1]
	v_pk_fma_f32 v[28:29], v[104:105], s[40:41], v[0:1] op_sel_hi:[1,0,1]
	v_pk_fma_f32 v[32:33], v[100:101], s[40:41], v[4:5] op_sel_hi:[1,0,1]
	v_cvt_pk_fp8_f32 v22, v28, v29
	v_cvt_pk_fp8_f32 v23, v32, v33
	v_pk_fma_f32 v[26:27], v[106:107], s[40:41], v[2:3] op_sel_hi:[1,0,1]
	v_pk_fma_f32 v[30:31], v[102:103], s[40:41], v[6:7] op_sel_hi:[1,0,1]
	v_cvt_pk_fp8_f32 v22, v26, v27 op_sel:[0,0,1]
	v_cvt_pk_fp8_f32 v23, v30, v31 op_sel:[0,0,1]
	v_pk_fma_f32 v[28:29], v[84:85], s[40:41], v[8:9] op_sel_hi:[1,0,1]
	v_pk_fma_f32 v[8:9], v[68:69], s[40:41], v[8:9] op_sel_hi:[1,0,1]
	v_permlane16_swap_b32_e32 v20, v22
	v_permlane16_swap_b32_e32 v21, v23
	global_store_dwordx4 v[24:25], v[20:23], off offset:128
	v_pk_fma_f32 v[24:25], v[92:93], s[40:41], v[10:11] op_sel_hi:[1,0,1]
	v_pk_fma_f32 v[10:11], v[72:73], s[40:41], v[10:11] op_sel_hi:[1,0,1]
	v_cvt_pk_fp8_f32 v20, v24, v25
	v_pk_fma_f32 v[22:23], v[94:95], s[40:41], v[14:15] op_sel_hi:[1,0,1]
	v_cvt_pk_fp8_f32 v21, v28, v29
	v_cvt_pk_fp8_f32 v20, v22, v23 op_sel:[0,0,1]
	v_cvt_pk_fp8_f32 v22, v10, v11
	v_cvt_pk_fp8_f32 v23, v8, v9
	v_pk_fma_f32 v[26:27], v[86:87], s[40:41], v[12:13] op_sel_hi:[1,0,1]
	v_pk_fma_f32 v[14:15], v[74:75], s[40:41], v[14:15] op_sel_hi:[1,0,1]
	v_pk_fma_f32 v[12:13], v[70:71], s[40:41], v[12:13] op_sel_hi:[1,0,1]
	v_cvt_pk_fp8_f32 v21, v26, v27 op_sel:[0,0,1]
	v_cvt_pk_fp8_f32 v22, v14, v15 op_sel:[0,0,1]
	v_cvt_pk_fp8_f32 v23, v12, v13 op_sel:[0,0,1]
	v_pk_fma_f32 v[14:15], v[96:97], s[40:41], v[0:1] op_sel_hi:[1,0,1]
	v_cvt_pk_fp8_f32 v8, v14, v15
	s_mov_b32 s2, 0x28000
	v_add_co_u32_e32 v12, vcc, s2, v18
	v_permlane16_swap_b32_e32 v20, v22
	v_permlane16_swap_b32_e32 v21, v23
	v_addc_co_u32_e32 v13, vcc, 0, v19, vcc
	v_pk_fma_f32 v[10:11], v[98:99], s[40:41], v[2:3] op_sel_hi:[1,0,1]
	global_store_dwordx4 v[12:13], v[20:23], off
	s_nop 0
	v_cvt_pk_fp8_f32 v8, v10, v11 op_sel:[0,0,1]
	v_pk_fma_f32 v[20:21], v[88:89], s[40:41], v[4:5] op_sel_hi:[1,0,1]
	v_pk_fma_f32 v[0:1], v[80:81], s[40:41], v[0:1] op_sel_hi:[1,0,1]
	v_pk_fma_f32 v[4:5], v[76:77], s[40:41], v[4:5] op_sel_hi:[1,0,1]
	v_cvt_pk_fp8_f32 v9, v20, v21
	v_cvt_pk_fp8_f32 v10, v0, v1
	v_cvt_pk_fp8_f32 v11, v4, v5
	v_pk_fma_f32 v[18:19], v[90:91], s[40:41], v[6:7] op_sel_hi:[1,0,1]
	v_pk_fma_f32 v[2:3], v[82:83], s[40:41], v[2:3] op_sel_hi:[1,0,1]
	v_pk_fma_f32 v[6:7], v[78:79], s[40:41], v[6:7] op_sel_hi:[1,0,1]
	v_cvt_pk_fp8_f32 v9, v18, v19 op_sel:[0,0,1]
	v_cvt_pk_fp8_f32 v10, v2, v3 op_sel:[0,0,1]
	v_cvt_pk_fp8_f32 v11, v6, v7 op_sel:[0,0,1]
	s_mov_b64 s[2:3], -1
	s_and_b64 vcc, exec, s[42:43]
	v_permlane16_swap_b32_e32 v8, v10
	v_permlane16_swap_b32_e32 v9, v11
	global_store_dwordx4 v[12:13], v[8:11], off offset:128
	s_cbranch_vccnz .LBB0_1101
	s_andn2_b64 vcc, exec, s[44:45]
	s_and_b32 s90, s89, 1
	s_cbranch_vccnz .LBB0_1129
	s_lshl_b64 s[2:3], s[50:51], 12
	s_add_u32 s37, s74, s2
	s_addc_u32 s40, s75, s3
	s_lshl_b32 s2, s36, 8
	s_ashr_i32 s3, s2, 31
	s_lshl_b64 s[2:3], s[2:3], 2
	s_add_u32 s2, s37, s2
	s_addc_u32 s3, s40, s3
	s_lshl_b32 s37, s90, 10
	s_add_i32 s37, s37, 0
	s_add_i32 m0, s37, 0x21400
	s_nop 0
	global_load_lds_dwordx4 v232, s[2:3]
